# v38: v36 + P0 prologue quant_block pass 1 (column maxima) loads software-pipelined one 8-load group ahead (second register set in v140-v175)
# baseline (speedup 1.0000x reference)
.Lpf1_a_loop:
	s_add_i32 s14, s14, 64
	v_add_u32_e32 v140, s14, v12
	v_add_u32_e32 v144, 8, v140
	v_add_u32_e32 v146, 16, v140
	v_add_u32_e32 v148, 24, v140
	v_add_u32_e32 v150, 32, v140
	v_add_u32_e32 v152, 40, v140
	v_add_u32_e32 v154, 48, v140
	v_add_u32_e32 v156, 56, v140
	v_ashrrev_i32_e32 v141, 31, v140
	v_ashrrev_i32_e32 v145, 31, v144
	v_ashrrev_i32_e32 v147, 31, v146
	v_ashrrev_i32_e32 v149, 31, v148
	v_ashrrev_i32_e32 v151, 31, v150
	v_ashrrev_i32_e32 v153, 31, v152
	v_ashrrev_i32_e32 v155, 31, v154
	v_ashrrev_i32_e32 v157, 31, v156
	v_lshlrev_b64 v[140:141], 14, v[140:141]
	v_lshlrev_b64 v[144:145], 14, v[144:145]
	v_lshlrev_b64 v[146:147], 14, v[146:147]
	v_lshlrev_b64 v[148:149], 14, v[148:149]
	v_lshlrev_b64 v[150:151], 14, v[150:151]
	v_lshlrev_b64 v[152:153], 14, v[152:153]
	v_lshlrev_b64 v[154:155], 14, v[154:155]
	v_lshlrev_b64 v[156:157], 14, v[156:157]
	v_lshl_add_u64 v[140:141], v[16:17], 0, v[140:141]
	v_lshl_add_u64 v[158:159], v[16:17], 0, v[144:145]
	v_lshl_add_u64 v[160:161], v[16:17], 0, v[146:147]
	v_lshl_add_u64 v[162:163], v[16:17], 0, v[148:149]
	v_lshl_add_u64 v[164:165], v[16:17], 0, v[150:151]
	v_lshl_add_u64 v[166:167], v[16:17], 0, v[152:153]
	v_lshl_add_u64 v[168:169], v[16:17], 0, v[154:155]
	v_lshl_add_u64 v[172:173], v[16:17], 0, v[156:157]
	global_load_dwordx4 v[144:147], v[140:141], off
	global_load_dwordx4 v[148:151], v[158:159], off
	global_load_dwordx4 v[152:155], v[160:161], off
	s_nop 0
	global_load_dwordx4 v[156:159], v[162:163], off
	s_nop 0
	global_load_dwordx4 v[160:163], v[164:165], off
	s_nop 0
	global_load_dwordx4 v[164:167], v[166:167], off
	s_nop 0
	global_load_dwordx4 v[168:171], v[168:169], off
	s_nop 0
	global_load_dwordx4 v[172:175], v[172:173], off
	s_waitcnt vmcnt(14)
	v_max3_f32 v7, v7, |v27|, |v31|
	v_max3_f32 v8, v8, |v26|, |v30|
	v_max3_f32 v18, v18, |v25|, |v29|
	v_max3_f32 v19, v19, |v24|, |v28|
	s_waitcnt vmcnt(12)
	v_max3_f32 v19, v19, |v32|, |v36|
	v_max3_f32 v18, v18, |v33|, |v37|
	v_max3_f32 v8, v8, |v34|, |v38|
	v_max3_f32 v7, v7, |v35|, |v39|
	s_waitcnt vmcnt(10)
	v_max3_f32 v7, v7, |v43|, |v47|
	v_max3_f32 v8, v8, |v42|, |v46|
	v_max3_f32 v18, v18, |v41|, |v45|
	v_max3_f32 v19, v19, |v40|, |v44|
	s_waitcnt vmcnt(8)
	v_max3_f32 v19, v19, |v48|, |v52|
	v_max3_f32 v18, v18, |v49|, |v53|
	v_max3_f32 v8, v8, |v50|, |v54|
	v_max3_f32 v7, v7, |v51|, |v55|
	s_add_i32 s14, s14, 64
	s_cmpk_eq_i32 s14, 0x200
	s_cbranch_scc1 .Lpf1_a_last
	v_add_u32_e32 v20, s14, v12
	v_add_u32_e32 v24, 8, v20
	v_add_u32_e32 v26, 16, v20
	v_add_u32_e32 v28, 24, v20
	v_add_u32_e32 v30, 32, v20
	v_add_u32_e32 v32, 40, v20
	v_add_u32_e32 v34, 48, v20
	v_add_u32_e32 v36, 56, v20
	v_ashrrev_i32_e32 v21, 31, v20
	v_ashrrev_i32_e32 v25, 31, v24
	v_ashrrev_i32_e32 v27, 31, v26
	v_ashrrev_i32_e32 v29, 31, v28
	v_ashrrev_i32_e32 v31, 31, v30
	v_ashrrev_i32_e32 v33, 31, v32
	v_ashrrev_i32_e32 v35, 31, v34
	v_ashrrev_i32_e32 v37, 31, v36
	v_lshlrev_b64 v[20:21], 14, v[20:21]
	v_lshlrev_b64 v[24:25], 14, v[24:25]
	v_lshlrev_b64 v[26:27], 14, v[26:27]
	v_lshlrev_b64 v[28:29], 14, v[28:29]
	v_lshlrev_b64 v[30:31], 14, v[30:31]
	v_lshlrev_b64 v[32:33], 14, v[32:33]
	v_lshlrev_b64 v[34:35], 14, v[34:35]
	v_lshlrev_b64 v[36:37], 14, v[36:37]
	v_lshl_add_u64 v[20:21], v[16:17], 0, v[20:21]
	v_lshl_add_u64 v[38:39], v[16:17], 0, v[24:25]
	v_lshl_add_u64 v[40:41], v[16:17], 0, v[26:27]
	v_lshl_add_u64 v[42:43], v[16:17], 0, v[28:29]
	v_lshl_add_u64 v[44:45], v[16:17], 0, v[30:31]
	v_lshl_add_u64 v[46:47], v[16:17], 0, v[32:33]
	v_lshl_add_u64 v[48:49], v[16:17], 0, v[34:35]
	v_lshl_add_u64 v[52:53], v[16:17], 0, v[36:37]
	global_load_dwordx4 v[24:27], v[20:21], off
	global_load_dwordx4 v[28:31], v[38:39], off
	global_load_dwordx4 v[32:35], v[40:41], off
	s_nop 0
	global_load_dwordx4 v[36:39], v[42:43], off
	s_nop 0
	global_load_dwordx4 v[40:43], v[44:45], off
	s_nop 0
	global_load_dwordx4 v[44:47], v[46:47], off
	s_nop 0
	global_load_dwordx4 v[48:51], v[48:49], off
	s_nop 0
	global_load_dwordx4 v[52:55], v[52:53], off
	s_waitcnt vmcnt(14)
	v_max3_f32 v7, v7, |v147|, |v151|
	v_max3_f32 v8, v8, |v146|, |v150|
	v_max3_f32 v18, v18, |v145|, |v149|
	v_max3_f32 v19, v19, |v144|, |v148|
	s_waitcnt vmcnt(12)
	v_max3_f32 v19, v19, |v152|, |v156|
	v_max3_f32 v18, v18, |v153|, |v157|
	v_max3_f32 v8, v8, |v154|, |v158|
	v_max3_f32 v7, v7, |v155|, |v159|
	s_waitcnt vmcnt(10)
	v_max3_f32 v7, v7, |v163|, |v167|
	v_max3_f32 v8, v8, |v162|, |v166|
	v_max3_f32 v18, v18, |v161|, |v165|
	v_max3_f32 v19, v19, |v160|, |v164|
	s_waitcnt vmcnt(8)
	v_max3_f32 v19, v19, |v168|, |v172|
	v_max3_f32 v18, v18, |v169|, |v173|
	v_max3_f32 v8, v8, |v170|, |v174|
	v_max3_f32 v7, v7, |v171|, |v175|
	s_branch .Lpf1_a_loop
.Lpf1_a_last:
	s_waitcnt vmcnt(6)
	v_max3_f32 v7, v7, |v147|, |v151|
	v_max3_f32 v8, v8, |v146|, |v150|
	v_max3_f32 v18, v18, |v145|, |v149|
	v_max3_f32 v19, v19, |v144|, |v148|
	s_waitcnt vmcnt(4)
	v_max3_f32 v19, v19, |v152|, |v156|
	v_max3_f32 v18, v18, |v153|, |v157|
	v_max3_f32 v8, v8, |v154|, |v158|
	v_max3_f32 v7, v7, |v155|, |v159|
	s_waitcnt vmcnt(2)
	v_max3_f32 v7, v7, |v163|, |v167|
	v_max3_f32 v8, v8, |v162|, |v166|
	v_max3_f32 v18, v18, |v161|, |v165|
	v_max3_f32 v19, v19, |v160|, |v164|
	s_waitcnt vmcnt(0)
	v_max3_f32 v19, v19, |v168|, |v172|
	v_max3_f32 v18, v18, |v169|, |v173|
	v_max3_f32 v8, v8, |v170|, |v174|
	v_max3_f32 v7, v7, |v171|, |v175|
	ds_swizzle_b32 v16, v19 offset:swizzle(SWAP,8)
	v_max_f32_e32 v17, v19, v19
	s_waitcnt lgkmcnt(0)
	v_max_f32_e32 v16, v16, v16
	v_max_f32_e32 v16, v17, v16
	ds_swizzle_b32 v17, v16 offset:swizzle(SWAP,16)
	s_waitcnt lgkmcnt(0)
	v_max_f32_e32 v17, v17, v17
	v_max_f32_e32 v16, v16, v17
	v_mov_b32_e32 v17, v16
	s_nop 1
	v_permlane32_swap_b32_e32 v16, v17
	s_and_saveexec_b64 s[14:15], s[6:7]
	v_max_f32_e32 v16, v16, v16
	v_max_f32_e32 v17, v17, v17
	v_max_f32_e32 v16, v16, v17
	v_add_u32_e32 v17, s20, v5
	ds_write_b32 v17, v16 offset:12288
	s_or_b64 exec, exec, s[14:15]
	ds_swizzle_b32 v16, v18 offset:swizzle(SWAP,8)
	v_max_f32_e32 v17, v18, v18
	s_waitcnt lgkmcnt(0)
	v_max_f32_e32 v16, v16, v16
	v_max_f32_e32 v16, v17, v16
	ds_swizzle_b32 v17, v16 offset:swizzle(SWAP,16)
	s_waitcnt lgkmcnt(0)
	v_max_f32_e32 v17, v17, v17
	v_max_f32_e32 v16, v16, v17
	v_mov_b32_e32 v17, v16
	s_nop 1
	v_permlane32_swap_b32_e32 v16, v17
	s_and_saveexec_b64 s[14:15], s[6:7]
	v_max_f32_e32 v16, v16, v16
	v_max_f32_e32 v17, v17, v17
	v_max_f32_e32 v16, v16, v17
	v_add_u32_e32 v17, s20, v5
	ds_write_b32 v17, v16 offset:12292
	s_or_b64 exec, exec, s[14:15]
	ds_swizzle_b32 v16, v8 offset:swizzle(SWAP,8)
	v_max_f32_e32 v8, v8, v8
	s_waitcnt lgkmcnt(0)
	v_max_f32_e32 v16, v16, v16
	v_max_f32_e32 v8, v8, v16
	ds_swizzle_b32 v16, v8 offset:swizzle(SWAP,16)
	s_waitcnt lgkmcnt(0)
	v_max_f32_e32 v16, v16, v16
	v_max_f32_e32 v8, v8, v16
	v_mov_b32_e32 v16, v8
	s_nop 1
	v_permlane32_swap_b32_e32 v8, v16
	s_and_saveexec_b64 s[14:15], s[6:7]
	v_max_f32_e32 v8, v8, v8
	v_max_f32_e32 v16, v16, v16
	v_max_f32_e32 v8, v8, v16
	v_add_u32_e32 v16, s20, v5
	ds_write_b32 v16, v8 offset:12296
	s_or_b64 exec, exec, s[14:15]
	ds_swizzle_b32 v8, v7 offset:swizzle(SWAP,8)
	v_max_f32_e32 v7, v7, v7
	s_waitcnt lgkmcnt(0)
	v_max_f32_e32 v8, v8, v8
	v_max_f32_e32 v7, v7, v8
	ds_swizzle_b32 v8, v7 offset:swizzle(SWAP,16)
	s_waitcnt lgkmcnt(0)
	v_max_f32_e32 v8, v8, v8
	v_max_f32_e32 v7, v7, v8
	v_mov_b32_e32 v8, v7
	s_nop 1
	v_permlane32_swap_b32_e32 v7, v8
	s_and_saveexec_b64 s[14:15], s[6:7]
	v_max_f32_e32 v7, v7, v7
	v_max_f32_e32 v8, v8, v8
	v_max_f32_e32 v7, v7, v8
	v_add_u32_e32 v8, s20, v5
	ds_write_b32 v8, v7 offset:12300
	s_or_b64 exec, exec, s[14:15]
	v_add_u32_e32 v7, 0x3000, v11
	s_waitcnt lgkmcnt(0)
	s_barrier
	ds_read2_b32 v[16:17], v7 offset1:32
	ds_read2_b32 v[18:19], v7 offset0:64 offset1:96
	ds_read2_b32 v[20:21], v7 offset0:128 offset1:160
	ds_read2_b32 v[24:25], v7 offset0:192 offset1:224
	v_readlane_b32 s14, v251, 6
	v_readlane_b32 s15, v251, 7
	s_add_u32 s12, s14, s12
	s_waitcnt lgkmcnt(3)
	v_max_f32_e32 v8, v17, v17
	v_max_f32_e32 v16, v16, v16
	v_max_f32_e32 v8, v16, v8
	s_waitcnt lgkmcnt(2)
	v_max3_f32 v8, v8, v18, v19
	s_addc_u32 s13, s15, s13
	s_waitcnt lgkmcnt(1)
	v_max3_f32 v8, v8, v20, v21
	s_waitcnt lgkmcnt(0)
	v_max3_f32 v8, v8, v24, v25
	v_lshl_add_u64 v[16:17], v[2:3], 2, s[12:13]
	s_and_saveexec_b64 s[12:13], s[8:9]
	s_cbranch_execz .LBB0_37
	v_mul_f32_e32 v18, 0x3c010204, v8
	global_store_dword v[16:17], v18, off

.Lpf1_b_loop:
	s_add_i32 s0, s0, 64
	v_add_u32_e32 v144, s0, v12
	v_mad_i64_i32 v[140:141], s[12:13], v144, s31, v[16:17]
	v_add_u32_e32 v145, 8, v144
	v_add_u32_e32 v146, 16, v144
	v_add_u32_e32 v147, 24, v144
	v_add_u32_e32 v150, 32, v144
	v_add_u32_e32 v151, 40, v144
	v_add_u32_e32 v154, 48, v144
	v_add_u32_e32 v144, 56, v144
	v_mad_i64_i32 v[148:149], s[12:13], v145, s31, v[16:17]
	v_mad_i64_i32 v[152:153], s[12:13], v146, s31, v[16:17]
	v_mad_i64_i32 v[156:157], s[12:13], v147, s31, v[16:17]
	v_mad_i64_i32 v[160:161], s[12:13], v150, s31, v[16:17]
	v_mad_i64_i32 v[164:165], s[12:13], v151, s31, v[16:17]
	v_mad_i64_i32 v[168:169], s[12:13], v154, s31, v[16:17]
	v_mad_i64_i32 v[172:173], s[12:13], v144, s31, v[16:17]
	global_load_dwordx4 v[144:147], v[140:141], off
	s_nop 0
	global_load_dwordx4 v[148:151], v[148:149], off
	s_nop 0
	global_load_dwordx4 v[152:155], v[152:153], off
	s_nop 0
	global_load_dwordx4 v[156:159], v[156:157], off
	s_nop 0
	global_load_dwordx4 v[160:163], v[160:161], off
	s_nop 0
	global_load_dwordx4 v[164:167], v[164:165], off
	s_nop 0
	global_load_dwordx4 v[168:171], v[168:169], off
	s_nop 0
	global_load_dwordx4 v[172:175], v[172:173], off
	s_waitcnt vmcnt(14)
	v_max3_f32 v7, v7, |v27|, |v31|
	v_max3_f32 v8, v8, |v26|, |v30|
	v_max3_f32 v18, v18, |v25|, |v29|
	v_max3_f32 v19, v19, |v24|, |v28|
	s_waitcnt vmcnt(12)
	v_max3_f32 v19, v19, |v32|, |v36|
	v_max3_f32 v18, v18, |v33|, |v37|
	v_max3_f32 v8, v8, |v34|, |v38|
	v_max3_f32 v7, v7, |v35|, |v39|
	s_waitcnt vmcnt(10)
	v_max3_f32 v7, v7, |v43|, |v47|
	v_max3_f32 v8, v8, |v42|, |v46|
	v_max3_f32 v18, v18, |v41|, |v45|
	v_max3_f32 v19, v19, |v40|, |v44|
	s_waitcnt vmcnt(8)
	v_max3_f32 v19, v19, |v48|, |v52|
	v_max3_f32 v18, v18, |v49|, |v53|
	v_max3_f32 v8, v8, |v50|, |v54|
	v_max3_f32 v7, v7, |v51|, |v55|
	s_add_i32 s0, s0, 64
	s_cmpk_eq_i32 s0, 0x200
	s_cbranch_scc1 .Lpf1_b_last
	v_add_u32_e32 v24, s0, v12
	v_mad_i64_i32 v[20:21], s[12:13], v24, s31, v[16:17]
	v_add_u32_e32 v25, 8, v24
	v_add_u32_e32 v26, 16, v24
	v_add_u32_e32 v27, 24, v24
	v_add_u32_e32 v30, 32, v24
	v_add_u32_e32 v31, 40, v24
	v_add_u32_e32 v34, 48, v24
	v_add_u32_e32 v24, 56, v24
	v_mad_i64_i32 v[28:29], s[12:13], v25, s31, v[16:17]
	v_mad_i64_i32 v[32:33], s[12:13], v26, s31, v[16:17]
	v_mad_i64_i32 v[36:37], s[12:13], v27, s31, v[16:17]
	v_mad_i64_i32 v[40:41], s[12:13], v30, s31, v[16:17]
	v_mad_i64_i32 v[44:45], s[12:13], v31, s31, v[16:17]
	v_mad_i64_i32 v[48:49], s[12:13], v34, s31, v[16:17]
	v_mad_i64_i32 v[52:53], s[12:13], v24, s31, v[16:17]
	global_load_dwordx4 v[24:27], v[20:21], off
	s_nop 0
	global_load_dwordx4 v[28:31], v[28:29], off
	s_nop 0
	global_load_dwordx4 v[32:35], v[32:33], off
	s_nop 0
	global_load_dwordx4 v[36:39], v[36:37], off
	s_nop 0
	global_load_dwordx4 v[40:43], v[40:41], off
	s_nop 0
	global_load_dwordx4 v[44:47], v[44:45], off
	s_nop 0
	global_load_dwordx4 v[48:51], v[48:49], off
	s_nop 0
	global_load_dwordx4 v[52:55], v[52:53], off
	s_waitcnt vmcnt(14)
	v_max3_f32 v7, v7, |v147|, |v151|
	v_max3_f32 v8, v8, |v146|, |v150|
	v_max3_f32 v18, v18, |v145|, |v149|
	v_max3_f32 v19, v19, |v144|, |v148|
	s_waitcnt vmcnt(12)
	v_max3_f32 v19, v19, |v152|, |v156|
	v_max3_f32 v18, v18, |v153|, |v157|
	v_max3_f32 v8, v8, |v154|, |v158|
	v_max3_f32 v7, v7, |v155|, |v159|
	s_waitcnt vmcnt(10)
	v_max3_f32 v7, v7, |v163|, |v167|
	v_max3_f32 v8, v8, |v162|, |v166|
	v_max3_f32 v18, v18, |v161|, |v165|
	v_max3_f32 v19, v19, |v160|, |v164|
	s_waitcnt vmcnt(8)
	v_max3_f32 v19, v19, |v168|, |v172|
	v_max3_f32 v18, v18, |v169|, |v173|
	v_max3_f32 v8, v8, |v170|, |v174|
	v_max3_f32 v7, v7, |v171|, |v175|
	s_branch .Lpf1_b_loop
.Lpf1_b_last:
	s_waitcnt vmcnt(6)
	v_max3_f32 v7, v7, |v147|, |v151|
	v_max3_f32 v8, v8, |v146|, |v150|
	v_max3_f32 v18, v18, |v145|, |v149|
	v_max3_f32 v19, v19, |v144|, |v148|
	s_waitcnt vmcnt(4)
	v_max3_f32 v19, v19, |v152|, |v156|
	v_max3_f32 v18, v18, |v153|, |v157|
	v_max3_f32 v8, v8, |v154|, |v158|
	v_max3_f32 v7, v7, |v155|, |v159|
	s_waitcnt vmcnt(2)
	v_max3_f32 v7, v7, |v163|, |v167|
	v_max3_f32 v8, v8, |v162|, |v166|
	v_max3_f32 v18, v18, |v161|, |v165|
	v_max3_f32 v19, v19, |v160|, |v164|
	s_waitcnt vmcnt(0)
	v_max3_f32 v19, v19, |v168|, |v172|
	v_max3_f32 v18, v18, |v169|, |v173|
	v_max3_f32 v8, v8, |v170|, |v174|
	v_max3_f32 v7, v7, |v171|, |v175|
	ds_swizzle_b32 v16, v19 offset:swizzle(SWAP,8)
	v_max_f32_e32 v17, v19, v19
	s_waitcnt lgkmcnt(0)
	v_max_f32_e32 v16, v16, v16
	v_max_f32_e32 v16, v17, v16
	ds_swizzle_b32 v17, v16 offset:swizzle(SWAP,16)
	s_waitcnt lgkmcnt(0)
	v_max_f32_e32 v17, v17, v17
	v_max_f32_e32 v16, v16, v17
	v_mov_b32_e32 v17, v16
	s_nop 1
	v_permlane32_swap_b32_e32 v16, v17
	s_and_saveexec_b64 s[12:13], s[6:7]
	v_max_f32_e32 v16, v16, v16
	v_max_f32_e32 v17, v17, v17
	v_max_f32_e32 v16, v16, v17
	v_add_u32_e32 v17, s20, v5
	ds_write_b32 v17, v16 offset:12288
	s_or_b64 exec, exec, s[12:13]
	ds_swizzle_b32 v16, v18 offset:swizzle(SWAP,8)
	v_max_f32_e32 v17, v18, v18
	s_waitcnt lgkmcnt(0)
	v_max_f32_e32 v16, v16, v16
	v_max_f32_e32 v16, v17, v16
	ds_swizzle_b32 v17, v16 offset:swizzle(SWAP,16)
	s_waitcnt lgkmcnt(0)
	v_max_f32_e32 v17, v17, v17
	v_max_f32_e32 v16, v16, v17
	v_mov_b32_e32 v17, v16
	s_nop 1
	v_permlane32_swap_b32_e32 v16, v17
	s_and_saveexec_b64 s[12:13], s[6:7]
	v_max_f32_e32 v16, v16, v16
	v_max_f32_e32 v17, v17, v17
	v_max_f32_e32 v16, v16, v17
	v_add_u32_e32 v17, s20, v5
	ds_write_b32 v17, v16 offset:12292
	s_or_b64 exec, exec, s[12:13]
	ds_swizzle_b32 v16, v8 offset:swizzle(SWAP,8)
	v_max_f32_e32 v8, v8, v8
	s_waitcnt lgkmcnt(0)
	v_max_f32_e32 v16, v16, v16
	v_max_f32_e32 v8, v8, v16
	ds_swizzle_b32 v16, v8 offset:swizzle(SWAP,16)
	s_waitcnt lgkmcnt(0)
	v_max_f32_e32 v16, v16, v16
	v_max_f32_e32 v8, v8, v16
	v_mov_b32_e32 v16, v8
	s_nop 1
	v_permlane32_swap_b32_e32 v8, v16
	s_and_saveexec_b64 s[12:13], s[6:7]
	v_max_f32_e32 v8, v8, v8
	v_max_f32_e32 v16, v16, v16
	v_max_f32_e32 v8, v8, v16
	v_add_u32_e32 v16, s20, v5
	ds_write_b32 v16, v8 offset:12296
	s_or_b64 exec, exec, s[12:13]
	ds_swizzle_b32 v8, v7 offset:swizzle(SWAP,8)
	v_max_f32_e32 v7, v7, v7
	s_waitcnt lgkmcnt(0)
	v_max_f32_e32 v8, v8, v8
	v_max_f32_e32 v7, v7, v8
	ds_swizzle_b32 v8, v7 offset:swizzle(SWAP,16)
	s_waitcnt lgkmcnt(0)
	v_max_f32_e32 v8, v8, v8
	v_max_f32_e32 v7, v7, v8
	v_mov_b32_e32 v8, v7
	s_nop 1
	v_permlane32_swap_b32_e32 v7, v8
	s_and_saveexec_b64 s[12:13], s[6:7]
	v_max_f32_e32 v7, v7, v7
	v_max_f32_e32 v8, v8, v8
	v_max_f32_e32 v7, v7, v8
	v_add_u32_e32 v8, s20, v5
	ds_write_b32 v8, v7 offset:12300
	s_or_b64 exec, exec, s[12:13]
	v_add_u32_e32 v7, 0x3000, v11
	s_waitcnt lgkmcnt(0)
	s_barrier
	ds_read2_b32 v[16:17], v7 offset1:32
	s_cmpk_lt_u32 s14, 0x6000
	s_cselect_b32 s0, s33, 0xffffa000
	s_cmpk_gt_u32 s14, 0x1fff
	s_cselect_b32 s0, s0, 0x7000
	s_add_i32 s12, s0, s14
	ds_read2_b32 v[18:19], v7 offset0:64 offset1:96
	ds_read2_b32 v[20:21], v7 offset0:128 offset1:160
	ds_read2_b32 v[24:25], v7 offset0:192 offset1:224
	s_ashr_i32 s13, s12, 31
	s_waitcnt lgkmcnt(3)
	v_max_f32_e32 v8, v17, v17
	v_max_f32_e32 v16, v16, v16
	s_lshl_b64 s[14:15], s[12:13], 2
	v_max_f32_e32 v8, v16, v8
	s_add_u32 s14, s16, s14
	s_waitcnt lgkmcnt(2)
	v_max3_f32 v8, v8, v18, v19
	s_addc_u32 s15, s17, s15
	s_waitcnt lgkmcnt(1)
	v_max3_f32 v8, v8, v20, v21
	s_waitcnt lgkmcnt(0)
	v_max3_f32 v8, v8, v24, v25
	v_lshl_add_u64 v[16:17], v[2:3], 2, s[14:15]
	s_and_saveexec_b64 s[14:15], s[8:9]
	s_cbranch_execz .LBB0_66
	v_mul_f32_e32 v18, 0x3c010204, v8
	global_store_dword v[16:17], v18, off

.Lpf1_c_loop:
	s_add_i32 s12, s12, 64
	v_add_u32_e32 v144, s12, v12
	v_mad_i64_i32 v[140:141], s[14:15], v144, s31, v[16:17]
	v_add_u32_e32 v145, 8, v144
	v_add_u32_e32 v146, 16, v144
	v_add_u32_e32 v147, 24, v144
	v_add_u32_e32 v150, 32, v144
	v_add_u32_e32 v151, 40, v144
	v_add_u32_e32 v154, 48, v144
	v_add_u32_e32 v144, 56, v144
	v_mad_i64_i32 v[148:149], s[14:15], v145, s31, v[16:17]
	v_mad_i64_i32 v[152:153], s[14:15], v146, s31, v[16:17]
	v_mad_i64_i32 v[156:157], s[14:15], v147, s31, v[16:17]
	v_mad_i64_i32 v[160:161], s[14:15], v150, s31, v[16:17]
	v_mad_i64_i32 v[164:165], s[14:15], v151, s31, v[16:17]
	v_mad_i64_i32 v[168:169], s[14:15], v154, s31, v[16:17]
	v_mad_i64_i32 v[172:173], s[14:15], v144, s31, v[16:17]
	global_load_dwordx4 v[144:147], v[140:141], off
	s_nop 0
	global_load_dwordx4 v[148:151], v[148:149], off
	s_nop 0
	global_load_dwordx4 v[152:155], v[152:153], off
	s_nop 0
	global_load_dwordx4 v[156:159], v[156:157], off
	s_nop 0
	global_load_dwordx4 v[160:163], v[160:161], off
	s_nop 0
	global_load_dwordx4 v[164:167], v[164:165], off
	s_nop 0
	global_load_dwordx4 v[168:171], v[168:169], off
	s_nop 0
	global_load_dwordx4 v[172:175], v[172:173], off
	s_waitcnt vmcnt(14)
	v_max3_f32 v7, v7, |v27|, |v31|
	v_max3_f32 v8, v8, |v26|, |v30|
	v_max3_f32 v18, v18, |v25|, |v29|
	v_max3_f32 v19, v19, |v24|, |v28|
	s_waitcnt vmcnt(12)
	v_max3_f32 v19, v19, |v32|, |v36|
	v_max3_f32 v18, v18, |v33|, |v37|
	v_max3_f32 v8, v8, |v34|, |v38|
	v_max3_f32 v7, v7, |v35|, |v39|
	s_waitcnt vmcnt(10)
	v_max3_f32 v7, v7, |v43|, |v47|
	v_max3_f32 v8, v8, |v42|, |v46|
	v_max3_f32 v18, v18, |v41|, |v45|
	v_max3_f32 v19, v19, |v40|, |v44|
	s_waitcnt vmcnt(8)
	v_max3_f32 v19, v19, |v48|, |v52|
	v_max3_f32 v18, v18, |v49|, |v53|
	v_max3_f32 v8, v8, |v50|, |v54|
	v_max3_f32 v7, v7, |v51|, |v55|
	s_add_i32 s12, s12, 64
	s_cmpk_eq_i32 s12, 0x200
	s_cbranch_scc1 .Lpf1_c_last
	v_add_u32_e32 v24, s12, v12
	v_mad_i64_i32 v[20:21], s[14:15], v24, s31, v[16:17]
	v_add_u32_e32 v25, 8, v24
	v_add_u32_e32 v26, 16, v24
	v_add_u32_e32 v27, 24, v24
	v_add_u32_e32 v30, 32, v24
	v_add_u32_e32 v31, 40, v24
	v_add_u32_e32 v34, 48, v24
	v_add_u32_e32 v24, 56, v24
	v_mad_i64_i32 v[28:29], s[14:15], v25, s31, v[16:17]
	v_mad_i64_i32 v[32:33], s[14:15], v26, s31, v[16:17]
	v_mad_i64_i32 v[36:37], s[14:15], v27, s31, v[16:17]
	v_mad_i64_i32 v[40:41], s[14:15], v30, s31, v[16:17]
	v_mad_i64_i32 v[44:45], s[14:15], v31, s31, v[16:17]
	v_mad_i64_i32 v[48:49], s[14:15], v34, s31, v[16:17]
	v_mad_i64_i32 v[52:53], s[14:15], v24, s31, v[16:17]
	global_load_dwordx4 v[24:27], v[20:21], off
	s_nop 0
	global_load_dwordx4 v[28:31], v[28:29], off
	s_nop 0
	global_load_dwordx4 v[32:35], v[32:33], off
	s_nop 0
	global_load_dwordx4 v[36:39], v[36:37], off
	s_nop 0
	global_load_dwordx4 v[40:43], v[40:41], off
	s_nop 0
	global_load_dwordx4 v[44:47], v[44:45], off
	s_nop 0
	global_load_dwordx4 v[48:51], v[48:49], off
	s_nop 0
	global_load_dwordx4 v[52:55], v[52:53], off
	s_waitcnt vmcnt(14)
	v_max3_f32 v7, v7, |v147|, |v151|
	v_max3_f32 v8, v8, |v146|, |v150|
	v_max3_f32 v18, v18, |v145|, |v149|
	v_max3_f32 v19, v19, |v144|, |v148|
	s_waitcnt vmcnt(12)
	v_max3_f32 v19, v19, |v152|, |v156|
	v_max3_f32 v18, v18, |v153|, |v157|
	v_max3_f32 v8, v8, |v154|, |v158|
	v_max3_f32 v7, v7, |v155|, |v159|
	s_waitcnt vmcnt(10)
	v_max3_f32 v7, v7, |v163|, |v167|
	v_max3_f32 v8, v8, |v162|, |v166|
	v_max3_f32 v18, v18, |v161|, |v165|
	v_max3_f32 v19, v19, |v160|, |v164|
	s_waitcnt vmcnt(8)
	v_max3_f32 v19, v19, |v168|, |v172|
	v_max3_f32 v18, v18, |v169|, |v173|
	v_max3_f32 v8, v8, |v170|, |v174|
	v_max3_f32 v7, v7, |v171|, |v175|
	s_branch .Lpf1_c_loop
.Lpf1_c_last:
	s_waitcnt vmcnt(6)
	v_max3_f32 v7, v7, |v147|, |v151|
	v_max3_f32 v8, v8, |v146|, |v150|
	v_max3_f32 v18, v18, |v145|, |v149|
	v_max3_f32 v19, v19, |v144|, |v148|
	s_waitcnt vmcnt(4)
	v_max3_f32 v19, v19, |v152|, |v156|
	v_max3_f32 v18, v18, |v153|, |v157|
	v_max3_f32 v8, v8, |v154|, |v158|
	v_max3_f32 v7, v7, |v155|, |v159|
	s_waitcnt vmcnt(2)
	v_max3_f32 v7, v7, |v163|, |v167|
	v_max3_f32 v8, v8, |v162|, |v166|
	v_max3_f32 v18, v18, |v161|, |v165|
	v_max3_f32 v19, v19, |v160|, |v164|
	s_waitcnt vmcnt(0)
	v_max3_f32 v19, v19, |v168|, |v172|
	v_max3_f32 v18, v18, |v169|, |v173|
	v_max3_f32 v8, v8, |v170|, |v174|
	v_max3_f32 v7, v7, |v171|, |v175|
	ds_swizzle_b32 v16, v19 offset:swizzle(SWAP,8)
	v_max_f32_e32 v17, v19, v19
	s_waitcnt lgkmcnt(0)
	v_max_f32_e32 v16, v16, v16
	v_max_f32_e32 v16, v17, v16
	ds_swizzle_b32 v17, v16 offset:swizzle(SWAP,16)
	s_waitcnt lgkmcnt(0)
	v_max_f32_e32 v17, v17, v17
	v_max_f32_e32 v17, v16, v17
	v_mov_b32_e32 v19, v17
	s_nop 1
	v_permlane32_swap_b32_e32 v17, v19
	v_add_u32_e32 v16, s20, v5
	s_and_saveexec_b64 s[12:13], s[6:7]
	v_max_f32_e32 v17, v17, v17
	v_max_f32_e32 v19, v19, v19
	v_max_f32_e32 v17, v17, v19
	ds_write_b32 v16, v17 offset:12288
	s_or_b64 exec, exec, s[12:13]
	ds_swizzle_b32 v17, v18 offset:swizzle(SWAP,8)
	v_max_f32_e32 v18, v18, v18
	s_waitcnt lgkmcnt(0)
	v_max_f32_e32 v17, v17, v17
	v_max_f32_e32 v17, v18, v17
	ds_swizzle_b32 v18, v17 offset:swizzle(SWAP,16)
	s_waitcnt lgkmcnt(0)
	v_max_f32_e32 v18, v18, v18
	v_max_f32_e32 v17, v17, v18
	v_mov_b32_e32 v18, v17
	s_nop 1
	v_permlane32_swap_b32_e32 v17, v18
	s_and_saveexec_b64 s[12:13], s[6:7]
	v_max_f32_e32 v17, v17, v17
	v_max_f32_e32 v18, v18, v18
	v_max_f32_e32 v17, v17, v18
	ds_write_b32 v16, v17 offset:12292
	s_or_b64 exec, exec, s[12:13]
	ds_swizzle_b32 v17, v8 offset:swizzle(SWAP,8)
	v_max_f32_e32 v8, v8, v8
	s_waitcnt lgkmcnt(0)
	v_max_f32_e32 v17, v17, v17
	v_max_f32_e32 v8, v8, v17
	ds_swizzle_b32 v17, v8 offset:swizzle(SWAP,16)
	s_waitcnt lgkmcnt(0)
	v_max_f32_e32 v17, v17, v17
	v_max_f32_e32 v8, v8, v17
	v_mov_b32_e32 v17, v8
	s_nop 1
	v_permlane32_swap_b32_e32 v8, v17
	s_and_saveexec_b64 s[12:13], s[6:7]
	v_max_f32_e32 v8, v8, v8
	v_max_f32_e32 v17, v17, v17
	v_max_f32_e32 v8, v8, v17
	ds_write_b32 v16, v8 offset:12296
	s_or_b64 exec, exec, s[12:13]
	ds_swizzle_b32 v8, v7 offset:swizzle(SWAP,8)
	v_max_f32_e32 v7, v7, v7
	s_waitcnt lgkmcnt(0)
	v_max_f32_e32 v8, v8, v8
	v_max_f32_e32 v7, v7, v8
	ds_swizzle_b32 v8, v7 offset:swizzle(SWAP,16)
	s_waitcnt lgkmcnt(0)
	v_max_f32_e32 v8, v8, v8
	v_max_f32_e32 v7, v7, v8
	v_mov_b32_e32 v8, v7
	s_nop 1
	v_permlane32_swap_b32_e32 v7, v8
	s_and_saveexec_b64 s[12:13], s[6:7]
	v_max_f32_e32 v7, v7, v7
	v_max_f32_e32 v8, v8, v8
	v_max_f32_e32 v7, v7, v8
	ds_write_b32 v16, v7 offset:12300
	s_or_b64 exec, exec, s[12:13]
	v_add_u32_e32 v7, 0x3000, v11
	s_waitcnt lgkmcnt(0)
	s_barrier
	ds_read2_b32 v[16:17], v7 offset1:32
	s_and_b32 s12, s0, 0xffffff00
	s_and_b32 s0, s0, 0xe0
	s_sub_i32 s0, s0, s12
	ds_read2_b32 v[18:19], v7 offset0:64 offset1:96
	ds_read2_b32 v[20:21], v7 offset0:128 offset1:160
	ds_read2_b32 v[24:25], v7 offset0:192 offset1:224
	s_addk_i32 s0, 0x6f00
	s_waitcnt lgkmcnt(3)
	v_max_f32_e32 v8, v17, v17
	v_max_f32_e32 v16, v16, v16
	s_lshl_b64 s[12:13], s[0:1], 2
	v_readlane_b32 s14, v251, 4
	v_max_f32_e32 v8, v16, v8
	s_add_u32 s12, s14, s12
	v_readlane_b32 s14, v251, 5
	s_waitcnt lgkmcnt(2)
	v_max3_f32 v8, v8, v18, v19
	s_addc_u32 s13, s14, s13
	s_waitcnt lgkmcnt(1)
	v_max3_f32 v8, v8, v20, v21
	s_waitcnt lgkmcnt(0)
	v_max3_f32 v8, v8, v24, v25
	v_lshl_add_u64 v[16:17], v[2:3], 2, s[12:13]
	s_and_saveexec_b64 s[12:13], s[8:9]
	s_cbranch_execz .LBB0_88
	v_mul_f32_e32 v18, 0x3c010204, v8
	global_store_dword v[16:17], v18, off
